# FoX prompt attention tile loop: two barriers per tile (after QK^T, before PV) with the two 4-wave halves offset by one barrier (MFMA segment of one half beside the softmax segment of the other); V til
# baseline (speedup 1.0000x reference)
.LBB0_710:
	v_readlane_b32 s0, v253, 51
	s_nop 3
	s_cmp_ge_u32 s0, 4
	s_cbranch_scc1 .Lfoxp_noextra
	s_barrier

.LBB0_711:
	s_xor_b64 s[80:81], s[0:1], -1
	s_and_b64 s[0:1], s[0:1], exec
	v_mov_b32_e32 v1, v0
	s_cselect_b32 s0, s93, s3
	v_readfirstlane_b32 s1, v1
	s_ashr_i32 s1, s1, 6
	s_lshl_b32 s2, s0, 8
	s_lshl_b32 s95, s1, 5
	v_and_b32_e32 v24, 31, v1
	s_add_i32 s95, s95, s2
	v_or_b32_e32 v2, s95, v24
	v_ashrrev_i32_e32 v3, 31, v2
	v_and_b32_e32 v5, 63, v1
	v_bfe_u32 v25, v1, 5, 1
	v_lshlrev_b64 v[134:135], 12, v[2:3]
	v_lshl_add_u64 v[6:7], s[38:39], 0, v[134:135]
	v_lshlrev_b32_e32 v8, 4, v25
	v_mov_b32_e32 v9, v4
	s_lshl_b32 s6, s1, 11
	v_lshlrev_b32_e32 v3, 4, v5
	v_lshl_add_u64 v[6:7], v[6:7], 0, v[8:9]
	v_or_b32_e32 v5, s6, v3
	global_load_dwordx4 v[102:105], v[6:7], off
	global_load_dwordx4 v[106:109], v[6:7], off offset:32
	global_load_dwordx4 v[110:113], v[6:7], off offset:64
	global_load_dwordx4 v[114:117], v[6:7], off offset:96
	global_load_dwordx4 v[118:121], v[6:7], off offset:128
	global_load_dwordx4 v[122:125], v[6:7], off offset:160
	global_load_dwordx4 v[126:129], v[6:7], off offset:192
	global_load_dwordx4 v[130:133], v[6:7], off offset:224
	v_ashrrev_i32_e32 v6, 31, v5
	v_add_u32_sdwa v6, v5, v6 dst_sel:DWORD dst_unused:UNUSED_PAD src0_sel:DWORD src1_sel:BYTE_3
	v_ashrrev_i32_e32 v6, 8, v6
	v_mul_i32_i24_e32 v7, 0x100, v6
	v_sub_u32_e32 v7, v5, v7
	v_ashrrev_i32_e32 v9, 4, v7
	v_bitop3_b32 v10, v9, v6, 15 bitop3:0x78
	v_ashrrev_i32_e32 v7, 31, v6
	v_lshlrev_b64 v[6:7], 12, v[6:7]
	v_lshlrev_b32_e32 v10, 3, v10
	s_bfe_i32 s2, s1, 0x10014
	v_lshl_add_u64 v[6:7], s[72:73], 0, v[6:7]
	v_ashrrev_i32_e32 v11, 31, v10
	s_lshr_b32 s2, s2, 24
	v_lshl_add_u64 v[6:7], v[10:11], 1, v[6:7]
	v_add_u32_e32 v10, s2, v5
	v_add_u32_e32 v10, 0x400, v10
	v_ashrrev_i32_e32 v10, 8, v10
	v_bitop3_b32 v9, v10, v9, 15 bitop3:0x6c
	v_ashrrev_i32_e32 v11, 31, v10
	v_lshlrev_b64 v[10:11], 12, v[10:11]
	v_lshlrev_b32_e32 v12, 3, v9
	v_lshl_add_u64 v[10:11], s[72:73], 0, v[10:11]
	v_ashrrev_i32_e32 v13, 31, v12
	v_lshl_add_u64 v[10:11], v[12:13], 1, v[10:11]
	v_ashrrev_i32_e32 v12, 8, v5
	v_lshlrev_b32_e32 v5, 2, v12
	s_lshl_b32 s1, s1, 1
	v_and_b32_e32 v9, 15, v1
	v_and_b32_e32 v5, 12, v5
	s_and_b32 s1, s1, 2
	v_ashrrev_i32_e32 v13, 31, v12
	v_bitop3_b32 v5, v5, v9, s1 bitop3:0x36
	v_lshlrev_b64 v[12:13], 12, v[12:13]
	s_or_b32 s1, s6, 0x400
	v_lshl_add_u64 v[12:13], s[74:75], 0, v[12:13]
	v_lshlrev_b32_e32 v14, 4, v5
	v_mov_b32_e32 v15, v4
	v_or_b32_e32 v3, s1, v3
	v_lshl_add_u64 v[12:13], v[12:13], 0, v[14:15]
	v_ashrrev_i32_e32 v14, 8, v3
	v_lshlrev_b32_e32 v3, 2, v14
	s_add_i32 s92, s6, 0
	v_and_b32_e32 v3, 12, v3
	s_bfe_u32 s1, s1, 0x2000a
	v_ashrrev_i32_e32 v15, 31, v14
	s_mov_b32 m0, s92
	s_add_i32 s2, 0, 0x12000
	v_bitop3_b32 v3, v3, v9, s1 bitop3:0x36
	v_lshlrev_b64 v[14:15], 12, v[14:15]
	global_load_lds_dwordx4 v[6:7], off
	s_add_i32 m0, s92, 0x400
	s_add_i32 s87, s2, s6
	v_lshl_add_u64 v[14:15], s[74:75], 0, v[14:15]
	v_lshlrev_b32_e32 v16, 4, v3
	v_mov_b32_e32 v17, v4
	global_load_lds_dwordx4 v[10:11], off
	s_mov_b32 m0, s87
	v_lshl_add_u64 v[14:15], v[14:15], 0, v[16:17]
	global_load_lds_dwordx4 v[12:13], off
	s_add_i32 m0, s87, 0x400
	v_lshl_add_u64 v[16:17], v[6:7], 0, s[4:5]
	global_load_lds_dwordx4 v[14:15], off
	s_add_i32 m0, s92, 0x4000
	v_lshl_add_u64 v[18:19], v[10:11], 0, s[4:5]
	global_load_lds_dwordx4 v[16:17], off
	s_add_i32 m0, s92, 0x4400
	v_lshl_add_u64 v[20:21], v[12:13], 0, s[4:5]
	global_load_lds_dwordx4 v[18:19], off
	v_lshl_add_u64 v[22:23], v[14:15], 0, s[4:5]
	s_lshl_b32 s1, s0, 2
	v_lshrrev_b32_e32 v9, 3, v1
	v_bfe_u32 v16, v1, 1, 1
	v_lshlrev_b32_e32 v136, 3, v25
	v_bfe_u32 v3, v1, 2, 2
	v_and_or_b32 v9, v9, 2, v16
	v_lshlrev_b32_e32 v17, 4, v1
	s_or_b32 s94, s1, 2
	s_movk_i32 s1, 0xf0
	v_or_b32_e32 v5, v136, v3
	v_lshlrev_b32_e32 v9, 4, v9
	v_lshl_add_u64 v[138:139], v[6:7], 0, s[96:97]
	v_and_b32_e32 v6, 0xf0, v17
	v_bitop3_b32 v146, v8, v17, s1 bitop3:0x78
	s_movk_i32 s1, 0x80
	v_lshlrev_b32_e32 v5, 8, v5
	v_lshlrev_b32_e32 v16, 3, v1
	v_bitop3_b32 v9, v9, v1, 32 bitop3:0x78
	v_lshlrev_b32_e32 v3, 6, v3
	v_bitop3_b32 v150, v8, v6, s1 bitop3:0x36
	s_movk_i32 s1, 0xa0
	s_waitcnt vmcnt(2)
	v_lshlrev_b32_e32 v1, 2, v25
	v_bitop3_b32 v151, v8, v6, s1 bitop3:0x36
	s_movk_i32 s1, 0xe0
	v_or3_b32 v3, v3, v5, v9
	v_and_or_b32 v5, v16, 8, s2
	v_mov_b32_e32 v16, v4
	v_mov_b32_e32 v17, v4
	v_lshl_add_u64 v[142:143], v[10:11], 0, s[96:97]
	v_lshl_add_u64 v[140:141], v[12:13], 0, s[4:5]
	v_lshl_add_u64 v[144:145], v[14:15], 0, s[4:5]
	s_waitcnt lgkmcnt(0)
	s_barrier
	v_readlane_b32 s6, v253, 51
	s_nop 3
	s_cmp_lt_u32 s6, 4
	s_cbranch_scc1 .Lfoxp_nostag
	s_barrier
.Lfoxp_nostag:
	v_lshl_add_u32 v137, v24, 8, 0
	v_bitop3_b32 v147, v8, v6, 32 bitop3:0x36
	v_bitop3_b32 v148, v8, v6, 64 bitop3:0x36
	v_bitop3_b32 v149, v8, v6, s89 bitop3:0x36
	v_bitop3_b32 v152, v8, v6, s88 bitop3:0x36
	v_bitop3_b32 v153, v8, v6, s1 bitop3:0x36
	v_add_u32_e32 v154, v5, v3
	v_add_u32_e32 v155, 0, v8
	v_sub_u32_e32 v156, v2, v1
	v_mov_b32_e32 v2, v4
	v_mov_b32_e32 v3, v4
	v_mov_b32_e32 v5, v4
	v_mov_b32_e32 v6, v4
	v_mov_b32_e32 v7, v4
	v_mov_b32_e32 v8, v4
	v_mov_b32_e32 v9, v4
	v_mov_b32_e32 v10, v4
	v_mov_b32_e32 v11, v4
	v_mov_b32_e32 v12, v4
	v_mov_b32_e32 v13, v4
	v_mov_b32_e32 v14, v4
	v_mov_b32_e32 v15, v4
	v_mov_b64_e32 v[68:69], v[16:17]
	v_mov_b64_e32 v[52:53], v[16:17]
	v_mov_b64_e32 v[36:37], v[16:17]
	s_lshl_b32 s33, s0, 10
	v_mov_b64_e32 v[66:67], v[14:15]
	v_mov_b64_e32 v[64:65], v[12:13]
	v_mov_b64_e32 v[62:63], v[10:11]
	v_mov_b64_e32 v[60:61], v[8:9]
	v_mov_b64_e32 v[58:59], v[6:7]
	v_mov_b64_e32 v[56:57], v[4:5]
	v_mov_b64_e32 v[54:55], v[2:3]
	v_mov_b64_e32 v[50:51], v[14:15]
	v_mov_b64_e32 v[48:49], v[12:13]
	v_mov_b64_e32 v[46:47], v[10:11]
	v_mov_b64_e32 v[44:45], v[8:9]
	v_mov_b64_e32 v[42:43], v[6:7]
	v_mov_b64_e32 v[40:41], v[4:5]
	v_mov_b64_e32 v[38:39], v[2:3]
	v_mov_b64_e32 v[34:35], v[14:15]
	v_mov_b64_e32 v[32:33], v[12:13]
	v_mov_b64_e32 v[30:31], v[10:11]
	v_mov_b64_e32 v[28:29], v[8:9]
	v_mov_b64_e32 v[26:27], v[6:7]
	v_mov_b64_e32 v[24:25], v[4:5]
	v_mov_b64_e32 v[22:23], v[2:3]
	v_mov_b64_e32 v[20:21], v[16:17]
	s_mov_b32 s85, 63
	s_mov_b32 s91, 2
	s_mov_b32 s36, 1
	s_or_b32 s84, s95, 31
	s_addk_i32 s33, 0x400
	s_mov_b32 s70, 0
	v_mov_b32_e32 v158, 0
	v_mov_b32_e32 v157, 0xf149f2ca
	v_mov_b64_e32 v[18:19], v[14:15]
	v_mov_b64_e32 v[16:17], v[12:13]
	v_mov_b64_e32 v[14:15], v[10:11]
	v_mov_b64_e32 v[12:13], v[8:9]
	v_mov_b64_e32 v[10:11], v[6:7]
	v_mov_b64_e32 v[8:9], v[4:5]
	v_mov_b64_e32 v[6:7], v[2:3]
	s_mov_b32 s0, 0
	s_mov_b32 s71, 0
.LBB0_712:
	s_cmp_ge_u32 s71, s94
	s_cselect_b64 s[82:83], -1, 0
	s_mov_b32 s89, s0
	s_and_b64 vcc, exec, s[82:83]
	s_cbranch_vccz .LBB0_719
	s_cmp_lg_u32 s71, s94
	s_cbranch_scc1 .Lfoxp_nodma
	s_lshl_b32 s0, s36, 14
	s_add_i32 s1, s87, s0
	s_add_i32 s6, s1, 0x400
	s_mov_b32 m0, s1
	s_nop 0
	global_load_lds_dwordx4 v[140:141], off
	s_mov_b32 m0, s6
	v_lshl_add_u64 v[140:141], v[140:141], 0, s[4:5]
	global_load_lds_dwordx4 v[144:145], off
	v_lshl_add_u64 v[144:145], v[144:145], 0, s[4:5]
.Lfoxp_nodma:
	s_sub_i32 s0, s85, 63
	s_cmp_gt_i32 s0, s84
	s_cbranch_scc0 .LBB0_720
.LBB0_714:
	s_cmp_lt_u32 s71, s94
	s_cbranch_scc1 .Lw_full_foxi
	s_cmp_eq_u32 s71, s94
	s_cbranch_scc1 .Lw_v_foxi
	s_waitcnt vmcnt(0)
	s_branch .Lw_done_foxi
.Lw_v_foxi:
	s_waitcnt vmcnt(2)
	s_branch .Lw_done_foxi

.Lw_done_foxi:
	s_barrier
	s_barrier
.LBB0_717:
	s_add_i32 s71, s71, 1
	s_addk_i32 s70, 0x100
	s_add_i32 s85, s85, 64
	s_cmp_lg_u32 s33, s70
	v_subrev_u32_e32 v156, 64, v156
	s_cbranch_scc0 .LBB0_710
	s_mov_b32 s0, s36
	s_mov_b32 s36, s91
	s_mov_b32 s91, s89
	s_branch .LBB0_712
.LBB0_719:
	s_lshl_b32 s0, s91, 14
	s_lshl_b32 s1, s36, 14
	s_add_i32 s1, s87, s1
	s_add_i32 s0, s92, s0
	s_add_i32 s7, s0, 0x400
	s_mov_b32 m0, s0
	s_add_i32 s6, s1, 0x400
	global_load_lds_dwordx4 v[138:139], off
	s_mov_b32 m0, s7
	v_lshl_add_u64 v[138:139], v[138:139], 0, s[4:5]
	global_load_lds_dwordx4 v[142:143], off
	s_mov_b32 m0, s1
	v_lshl_add_u64 v[142:143], v[142:143], 0, s[4:5]
	global_load_lds_dwordx4 v[140:141], off
	s_mov_b32 m0, s6
	v_lshl_add_u64 v[140:141], v[140:141], 0, s[4:5]
	global_load_lds_dwordx4 v[144:145], off
	v_lshl_add_u64 v[144:145], v[144:145], 0, s[4:5]
	s_sub_i32 s0, s85, 63
	s_cmp_gt_i32 s0, s84
	s_cbranch_scc1 .LBB0_714
.LBB0_720:
	s_lshl_b32 s37, s89, 14
	v_add_u32_e32 v2, s37, v137
	v_add_u32_e32 v3, v2, v146
	ds_read_b128 v[70:73], v3
	ds_read_b128 v[74:77], v3 offset:8192
	v_add_u32_e32 v3, v2, v147
	ds_read_b128 v[160:163], v3
	ds_read_b128 v[164:167], v3 offset:8192
	v_add_u32_e32 v3, v2, v148
	ds_read_b128 v[168:171], v3
	ds_read_b128 v[172:175], v3 offset:8192
	v_add_u32_e32 v3, v2, v149
	ds_read_b128 v[176:179], v3
	ds_read_b128 v[180:183], v3 offset:8192
	v_add_u32_e32 v3, v2, v150
	ds_read_b128 v[184:187], v3
	ds_read_b128 v[188:191], v3 offset:8192
	v_add_u32_e32 v3, v2, v151
	ds_read_b128 v[192:195], v3
	ds_read_b128 v[196:199], v3 offset:8192
	v_add_u32_e32 v3, v2, v152
	v_add_u32_e32 v2, v2, v153
	ds_read_b128 v[200:203], v3
	ds_read_b128 v[204:207], v3 offset:8192
	ds_read_b128 v[208:211], v2
	ds_read_b128 v[216:219], v2 offset:8192
	s_waitcnt lgkmcnt(0)
	v_mfma_f32_32x32x16_bf16 v[86:101], v[70:73], v[102:105], 0
	v_mfma_f32_32x32x16_bf16 v[70:85], v[74:77], v[102:105], 0
	v_mfma_f32_32x32x16_bf16 v[86:101], v[160:163], v[106:109], v[86:101]
	v_mfma_f32_32x32x16_bf16 v[70:85], v[164:167], v[106:109], v[70:85]
	v_mfma_f32_32x32x16_bf16 v[86:101], v[168:171], v[110:113], v[86:101]
	v_mfma_f32_32x32x16_bf16 v[70:85], v[172:175], v[110:113], v[70:85]
	v_mfma_f32_32x32x16_bf16 v[86:101], v[176:179], v[114:117], v[86:101]
	v_mfma_f32_32x32x16_bf16 v[70:85], v[180:183], v[114:117], v[70:85]
	v_mfma_f32_32x32x16_bf16 v[86:101], v[184:187], v[118:121], v[86:101]
	v_mfma_f32_32x32x16_bf16 v[70:85], v[188:191], v[118:121], v[70:85]
	v_mfma_f32_32x32x16_bf16 v[86:101], v[192:195], v[122:125], v[86:101]
	v_mfma_f32_32x32x16_bf16 v[70:85], v[196:199], v[122:125], v[70:85]
	v_mfma_f32_32x32x16_bf16 v[86:101], v[200:203], v[126:129], v[86:101]
	v_mfma_f32_32x32x16_bf16 v[70:85], v[204:207], v[126:129], v[70:85]
	v_mfma_f32_32x32x16_bf16 v[86:101], v[208:211], v[130:133], v[86:101]
	v_mfma_f32_32x32x16_bf16 v[70:85], v[216:219], v[130:133], v[70:85]
	s_cmp_lt_u32 s71, s94
	s_cbranch_scc1 .Lw_full_foxa
	s_cmp_eq_u32 s71, s94
	s_cbranch_scc1 .Lw_v_foxa
	s_waitcnt vmcnt(0)
	s_branch .Lw_done_foxa

.Lw_done_foxa:
	s_barrier
	v_add_u32_e32 v2, s70, v155
	v_add_u32_e32 v3, 0x1e000, v2
	v_add_u32_e32 v5, 0x1e080, v2
	ds_read_b128 v[160:163], v3
	ds_read_b128 v[164:167], v5
	v_add_u32_e32 v3, 0x1e020, v2
	v_add_u32_e32 v5, 0x1e0a0, v2
	ds_read_b128 v[168:171], v3
	ds_read_b128 v[172:175], v5
	v_add_u32_e32 v3, 0x1e040, v2
	v_add_u32_e32 v5, 0x1e0c0, v2
	ds_read_b128 v[176:179], v3
	ds_read_b128 v[180:183], v5
	v_add_u32_e32 v3, 0x1e060, v2
	v_add_u32_e32 v2, 0x1e0e0, v2
	ds_read_b128 v[184:187], v3
	ds_read_b128 v[188:191], v2
	s_waitcnt lgkmcnt(0)
	v_fma_f32 v2, v100, s86, -v186
	v_fma_f32 v3, v101, s86, -v187
	v_fma_f32 v88, v88, s86, -v162
	v_fma_f32 v89, v89, s86, -v163
	v_fma_f32 v86, v86, s86, -v160
	v_fma_f32 v87, v87, s86, -v161
	v_fma_f32 v98, v98, s86, -v184
	v_fma_f32 v99, v99, s86, -v185
	v_fma_f32 v96, v96, s86, -v178
	v_fma_f32 v97, v97, s86, -v179
	v_fma_f32 v94, v94, s86, -v176
	v_fma_f32 v95, v95, s86, -v177
	v_fma_f32 v92, v92, s86, -v170
	v_fma_f32 v93, v93, s86, -v171
	v_fma_f32 v90, v90, s86, -v168
	v_fma_f32 v91, v91, s86, -v169
	v_fma_f32 v84, v84, s86, -v190
	v_fma_f32 v85, v85, s86, -v191
	v_fma_f32 v82, v82, s86, -v188
	v_fma_f32 v83, v83, s86, -v189
	v_fma_f32 v80, v80, s86, -v182
	v_fma_f32 v81, v81, s86, -v183
	v_fma_f32 v78, v78, s86, -v180
	v_fma_f32 v79, v79, s86, -v181
	v_fma_f32 v76, v76, s86, -v174
	v_fma_f32 v77, v77, s86, -v175
	v_fma_f32 v74, v74, s86, -v172
	v_fma_f32 v75, v75, s86, -v173
	v_fma_f32 v72, v72, s86, -v166
	v_fma_f32 v73, v73, s86, -v167
	s_cmp_le_i32 s85, s95
	v_fma_f32 v70, v70, s86, -v164
	v_fma_f32 v71, v71, s86, -v165
	s_cbranch_scc1 .LBB0_722
	v_cmp_gt_i32_e64 s[66:67], 26, v156
	v_cmp_gt_i32_e64 s[68:69], 27, v156
	v_cmp_gt_i32_e64 s[64:65], 25, v156
	s_and_b64 s[66:67], s[68:69], s[66:67]
	v_cmp_gt_i32_e64 s[62:63], 24, v156
	s_and_b64 s[64:65], s[66:67], s[64:65]
	v_cmp_gt_i32_e64 s[60:61], 19, v156
	s_and_b64 s[62:63], s[64:65], s[62:63]
	v_cmp_gt_i32_e64 s[58:59], 18, v156
	s_and_b64 s[60:61], s[62:63], s[60:61]
	v_cmp_gt_i32_e64 s[56:57], 17, v156
	s_and_b64 s[58:59], s[60:61], s[58:59]
	v_cmp_gt_i32_e64 s[54:55], 16, v156
	s_and_b64 s[56:57], s[58:59], s[56:57]
	v_cmp_gt_i32_e64 s[52:53], 11, v156
	s_and_b64 s[54:55], s[56:57], s[54:55]
	v_cmp_gt_i32_e64 s[50:51], 10, v156
	s_and_b64 s[52:53], s[54:55], s[52:53]
	v_cmp_gt_i32_e64 s[48:49], 9, v156
	s_and_b64 s[50:51], s[52:53], s[50:51]
	v_cmp_gt_i32_e64 s[46:47], 8, v156
	s_and_b64 s[48:49], s[50:51], s[48:49]
	v_cmp_gt_i32_e64 s[44:45], 3, v156
	s_and_b64 s[46:47], s[48:49], s[46:47]
	v_cmp_gt_i32_e64 s[42:43], 2, v156
	s_and_b64 s[44:45], s[46:47], s[44:45]
	v_cmp_gt_i32_e64 s[40:41], 1, v156
	s_and_b64 s[42:43], s[44:45], s[42:43]
	v_cmp_gt_i32_e64 s[0:1], 0, v156
	s_and_b64 s[40:41], s[42:43], s[40:41]
	s_and_b64 s[0:1], s[40:41], s[0:1]
	v_cmp_gt_i32_e64 s[34:35], 58, v156
	v_cndmask_b32_e64 v86, v86, v247, s[0:1]
	v_cmp_gt_i32_e64 s[0:1], 59, v156
	v_cmp_gt_i32_e64 s[30:31], 57, v156
	v_cmp_gt_i32_e64 s[28:29], 56, v156
	v_cndmask_b32_e64 v85, v85, v247, s[0:1]
	s_and_b64 s[0:1], s[0:1], s[34:35]
	v_cndmask_b32_e64 v84, v84, v247, s[0:1]
	s_and_b64 s[0:1], s[0:1], s[30:31]
	v_cmp_gt_i32_e64 s[26:27], 51, v156
	v_cndmask_b32_e64 v83, v83, v247, s[0:1]
	s_and_b64 s[0:1], s[0:1], s[28:29]
	v_cmp_gt_i32_e64 s[24:25], 50, v156
	v_cndmask_b32_e64 v82, v82, v247, s[0:1]
	s_and_b64 s[0:1], s[0:1], s[26:27]
	v_cmp_gt_i32_e64 s[22:23], 49, v156
	v_cndmask_b32_e64 v81, v81, v247, s[0:1]
	s_and_b64 s[0:1], s[0:1], s[24:25]
	v_cmp_gt_i32_e64 s[20:21], 48, v156
	v_cndmask_b32_e64 v80, v80, v247, s[0:1]
	s_and_b64 s[0:1], s[0:1], s[22:23]
	v_cmp_gt_i32_e64 s[18:19], 43, v156
	v_cndmask_b32_e64 v79, v79, v247, s[0:1]
	s_and_b64 s[0:1], s[0:1], s[20:21]
	v_cmp_gt_i32_e64 s[16:17], 42, v156
	v_cndmask_b32_e64 v78, v78, v247, s[0:1]
	s_and_b64 s[0:1], s[0:1], s[18:19]
	v_cmp_gt_i32_e64 s[14:15], 41, v156
	v_cndmask_b32_e64 v77, v77, v247, s[0:1]
	s_and_b64 s[0:1], s[0:1], s[16:17]
	v_cmp_gt_i32_e64 s[12:13], 40, v156
	v_cndmask_b32_e64 v76, v76, v247, s[0:1]
	s_and_b64 s[0:1], s[0:1], s[14:15]
	v_cmp_gt_i32_e64 s[10:11], 35, v156
	v_cndmask_b32_e64 v75, v75, v247, s[0:1]
	s_and_b64 s[0:1], s[0:1], s[12:13]
	v_cmp_gt_i32_e64 s[8:9], 34, v156
	v_cndmask_b32_e64 v74, v74, v247, s[0:1]
	s_and_b64 s[0:1], s[0:1], s[10:11]
	v_cmp_gt_i32_e64 s[6:7], 33, v156
	v_cndmask_b32_e64 v73, v73, v247, s[0:1]
	s_and_b64 s[0:1], s[0:1], s[8:9]
	v_cmp_gt_i32_e32 vcc, 32, v156
	v_cndmask_b32_e64 v72, v72, v247, s[0:1]
	s_and_b64 s[0:1], s[0:1], s[6:7]
	s_and_b64 vcc, s[0:1], vcc
	v_cndmask_b32_e64 v3, v3, v247, s[68:69]
	v_cndmask_b32_e64 v2, v2, v247, s[66:67]
	v_cndmask_b32_e64 v99, v99, v247, s[64:65]
	v_cndmask_b32_e64 v98, v98, v247, s[62:63]
	v_cndmask_b32_e64 v97, v97, v247, s[60:61]
	v_cndmask_b32_e64 v96, v96, v247, s[58:59]
	v_cndmask_b32_e64 v95, v95, v247, s[56:57]
	v_cndmask_b32_e64 v94, v94, v247, s[54:55]
	v_cndmask_b32_e64 v93, v93, v247, s[52:53]
	v_cndmask_b32_e64 v92, v92, v247, s[50:51]
	s_mov_b32 s51, 0x40c000
	v_cndmask_b32_e64 v91, v91, v247, s[48:49]
	s_mov_b64 s[48:49], 0x7ffff
	v_cndmask_b32_e64 v90, v90, v247, s[46:47]
	s_mov_b32 s47, 0x120000
	v_cndmask_b32_e64 v89, v89, v247, s[44:45]
	v_cndmask_b32_e64 v88, v88, v247, s[42:43]
	v_cndmask_b32_e64 v87, v87, v247, s[40:41]
	s_mov_b32 s40, 0x41000000
	v_cndmask_b32_e64 v71, v71, v247, s[0:1]
	v_cndmask_b32_e32 v70, v70, v247, vcc

.LBB0_724:
	v_add_f32_e32 v174, v85, v101
	v_fmac_f32_e32 v174, v158, v2
	v_cvt_pk_bf16_f32 v86, v86, v87
	v_cvt_pk_bf16_f32 v87, v88, v89
	v_cvt_pk_bf16_f32 v88, v90, v91
	v_cvt_pk_bf16_f32 v89, v92, v100
	v_cvt_pk_bf16_f32 v90, v93, v94
	v_cvt_pk_bf16_f32 v91, v95, v96
	v_cvt_pk_bf16_f32 v92, v97, v98
	v_cvt_pk_bf16_f32 v93, v99, v84
	v_cvt_pk_bf16_f32 v70, v5, v70
	v_cvt_pk_bf16_f32 v71, v71, v72
	v_cvt_pk_bf16_f32 v72, v73, v74
	v_cvt_pk_bf16_f32 v73, v75, v77
	v_cvt_pk_bf16_f32 v74, v76, v78
	v_cvt_pk_bf16_f32 v75, v79, v80
	v_cvt_pk_bf16_f32 v76, v81, v82
	v_cvt_pk_bf16_f32 v77, v83, v3
	s_barrier
	v_add_u32_e32 v2, s37, v154
	ds_read_b64_tr_b16 v[78:79], v2 offset:0
	v_xor_b32_e32 v3, 0x410, v2
	ds_read_b64_tr_b16 v[80:81], v3 offset:0
	ds_read_b64_tr_b16 v[82:83], v2 offset:0x1000
	ds_read_b64_tr_b16 v[84:85], v3 offset:0x1000
	ds_read_b64_tr_b16 v[94:95], v2 offset:0x2000
	ds_read_b64_tr_b16 v[96:97], v3 offset:0x2000
	ds_read_b64_tr_b16 v[98:99], v2 offset:0x3000
	ds_read_b64_tr_b16 v[100:101], v3 offset:0x3000
	v_xor_b32_e32 v5, 64, v2
	ds_read_b64_tr_b16 v[158:159], v5 offset:0
	v_xor_b32_e32 v175, 0x450, v2
	ds_read_b64_tr_b16 v[160:161], v175 offset:0
	ds_read_b64_tr_b16 v[162:163], v5 offset:0x1000
	ds_read_b64_tr_b16 v[164:165], v175 offset:0x1000
	ds_read_b64_tr_b16 v[166:167], v5 offset:0x2000
	ds_read_b64_tr_b16 v[168:169], v175 offset:0x2000
	ds_read_b64_tr_b16 v[170:171], v5 offset:0x3000
	ds_read_b64_tr_b16 v[172:173], v175 offset:0x3000
	s_waitcnt lgkmcnt(0)
	v_permlane32_swap_b32_e32 v86, v88
	v_permlane32_swap_b32_e32 v87, v89
	v_permlane32_swap_b32_e32 v90, v92
	v_permlane32_swap_b32_e32 v91, v93
	v_permlane32_swap_b32_e32 v70, v72
	v_permlane32_swap_b32_e32 v71, v73
	v_permlane32_swap_b32_e32 v74, v76
	v_permlane32_swap_b32_e32 v75, v77
	v_mfma_f32_32x32x16_bf16 v[54:69], v[78:81], v[86:89], v[54:69]
	v_xor_b32_e32 v3, 0x80, v2
	ds_read_b64_tr_b16 v[78:79], v3 offset:0
	v_xor_b32_e32 v5, 0x490, v2
	ds_read_b64_tr_b16 v[80:81], v5 offset:0
	v_mfma_f32_32x32x16_bf16 v[38:53], v[158:161], v[86:89], v[38:53]
	v_mfma_f32_32x32x16_bf16 v[54:69], v[82:85], v[90:93], v[54:69]
	ds_read_b64_tr_b16 v[82:83], v3 offset:0x1000
	ds_read_b64_tr_b16 v[84:85], v5 offset:0x1000
	v_mfma_f32_32x32x16_bf16 v[38:53], v[162:165], v[90:93], v[38:53]
	v_mfma_f32_32x32x16_bf16 v[54:69], v[94:97], v[70:73], v[54:69]
	ds_read_b64_tr_b16 v[94:95], v3 offset:0x2000
	ds_read_b64_tr_b16 v[96:97], v5 offset:0x2000
	v_mfma_f32_32x32x16_bf16 v[38:53], v[166:169], v[70:73], v[38:53]
	v_mfma_f32_32x32x16_bf16 v[54:69], v[98:101], v[74:77], v[54:69]
	ds_read_b64_tr_b16 v[98:99], v3 offset:0x3000
	ds_read_b64_tr_b16 v[100:101], v5 offset:0x3000
	v_mfma_f32_32x32x16_bf16 v[38:53], v[170:173], v[74:77], v[38:53]
	v_xor_b32_e32 v172, 0xc0, v2
	ds_read_b64_tr_b16 v[158:159], v172 offset:0
	v_xor_b32_e32 v2, 0x4d0, v2
	ds_read_b64_tr_b16 v[160:161], v2 offset:0
	ds_read_b64_tr_b16 v[162:163], v172 offset:0x1000
	ds_read_b64_tr_b16 v[164:165], v2 offset:0x1000
	ds_read_b64_tr_b16 v[166:167], v172 offset:0x2000
	ds_read_b64_tr_b16 v[168:169], v2 offset:0x2000
	ds_read_b64_tr_b16 v[170:171], v172 offset:0x3000
	ds_read_b64_tr_b16 v[172:173], v2 offset:0x3000
	s_waitcnt lgkmcnt(0)
	v_mfma_f32_32x32x16_bf16 v[22:37], v[78:81], v[86:89], v[22:37]
	v_mfma_f32_32x32x16_bf16 v[6:21], v[158:161], v[86:89], v[6:21]
	v_mov_b32_e32 v158, v174
	v_mfma_f32_32x32x16_bf16 v[22:37], v[82:85], v[90:93], v[22:37]
	v_mfma_f32_32x32x16_bf16 v[6:21], v[162:165], v[90:93], v[6:21]
	v_mfma_f32_32x32x16_bf16 v[22:37], v[94:97], v[70:73], v[22:37]
	v_mfma_f32_32x32x16_bf16 v[6:21], v[166:169], v[70:73], v[6:21]
	v_mfma_f32_32x32x16_bf16 v[22:37], v[98:101], v[74:77], v[22:37]
	v_mfma_f32_32x32x16_bf16 v[6:21], v[170:173], v[74:77], v[6:21]
	s_branch .LBB0_717
